# P3 chain epilogue rewritten: all gate loads issued up front, in-place accumulator scaling, register permutation removed
# speedup vs baseline: 1.0057x; 1.0057x over previous
; #define PG8_BAR __builtin_amdgcn_s_barrier()
; #define PG8_BAR __builtin_amdgcn_s_barrier()
; template <class Epi, class Sched, bool ALIGN_EPI, bool SP2>
; __device__ __forceinline__ void gemm_phase(LAS unsigned char* lds, const int K, const Sched& S, const Epi& E) {
;     ...
;         if constexpr (!Epi::AFTER_DRAIN) { if constexpr (Epi::CHAIN) E.chain(acc, cur, wr, wc, fr, fq); else E(acc, cur, wr, wc, fr, fq); }
;         if (!has_next) break;
;         if (!(Epi::CHAIN && nxt.sub != 0))
; #pragma unroll
;         for (int a = 0; a < 2; ++a)
; #pragma unroll
;             for (int b = 0; b < 2; ++b)
; #pragma unroll
;                 for (int m = 0; m < 4; ++m)
; #pragma unroll
;                     for (int n = 0; n < 2; ++n) acc[a][b][m][n] = (f32x4){0.f, 0.f, 0.f, 0.f};
;         cur = nxt; cA = nA; cB = nB; ++ui;
;         if constexpr (ALIGN_EPI) { if (wr == 1) PG8_BAR; }
.LBB0_860:
	s_and_b64 vcc, exec, s[0:1]
	s_mov_b32 s39, s28
	s_mov_b32 s38, s24
	s_mov_b32 s40, s26
	s_mov_b64 s[42:43], s[36:37]
	s_mov_b64 s[44:45], s[30:31]
	s_cbranch_vccnz .LBB0_976

; __device__ __forceinline__ float frcp(float x) { return __builtin_amdgcn_rcpf(x); }
;     static __device__ __forceinline__ float ub(unsigned w, int i) { return (float)((w >> (8 * i)) & 0xffu); }
;     __device__ __forceinline__ void chain(Acc& acc, const Unit& u, int wr, int wc, int fr, int fq) const {
;         const int row0 = u.pm * BM + wr * 64 + fr; const int col0 = u.pn * BM + wc * 32 + 8 * fq;
;         const int sub = u.sub, subn = (u.sub < 2) ? u.sub + 1 : 2;
; #pragma unroll
;         for (int ai = 0; ai < 2; ++ai) {
;             u32x2 g[4][2], h[4][2];
; #pragma unroll
;             for (int m = 0; m < 4; ++m)
; #pragma unroll
;                 for (int bj = 0; bj < 2; ++bj) { const unsigned char* p = GT + (size_t)(row0 + ai * HALF + m * 16) * NGT + col0 + bj * HALF;
;                     g[m][bj] = *(const u32x2*)(p + sub * DM); h[m][bj] = *(const u32x2*)(p + subn * DM); }
; #pragma unroll
;             for (int m = 0; m < 4; ++m)
; #pragma unroll
;                 for (int bj = 0; bj < 2; ++bj) { const u32x2 gg = g[m][bj], hh = h[m][bj];
;                     float sc[8];
;                     if (sub < 2) {
; #pragma unroll
;                         for (int e = 0; e < 8; ++e) sc[e] = ub(e < 4 ? gg.x : gg.y, e & 3) * frcp(ub(e < 4 ? hh.x : hh.y, e & 3));
;                     } else {
; #pragma unroll
;                         for (int e = 0; e < 8; ++e) sc[e] = ub(e < 4 ? gg.x : gg.y, e & 3) * (1.0f / 255.0f);
;                     }
;                     f32x4 a0 = acc[ai][bj][m][0], a1 = acc[ai][bj][m][1];
;                     a0 *= (f32x4){sc[0], sc[1], sc[2], sc[3]}; a1 *= (f32x4){sc[4], sc[5], sc[6], sc[7]};
;                     if (sub < 2) { acc[ai][bj][m][0] = a0; acc[ai][bj][m][1] = a1; }
.LBB0_875:
	v_lshl_add_u32 v234, s40, 8, v206
	v_lshl_or_b32 v235, s38, 8, v208
	s_lshl_b32 s25, s39, 11
	s_add_u32 s40, s10, s25
	s_addc_u32 s41, s11, 0
	s_add_u32 s38, s40, 0x800
	s_addc_u32 s39, s41, 0
	v_mad_u32_u24 v236, v234, s54, v235
	v_add_u32_e32 v237, 0x18000, v236
	v_add_u32_e32 v238, 0x30000, v236
	v_add_u32_e32 v239, 0x48000, v236
	v_add_u32_e32 v240, 0xc0000, v236
	v_add_u32_e32 v241, 0xd8000, v236
	v_add_u32_e32 v242, 0xf0000, v236
	v_add_u32_e32 v243, 0x108000, v236
	s_cmp_gt_i32 s25, 0x800
	s_cbranch_scc1 .Lp3c_last
	global_load_dwordx2 v[190:191], v236, s[40:41]
	global_load_dwordx2 v[46:47], v236, s[38:39]
	global_load_dwordx2 v[192:193], v236, s[40:41] offset:128
	global_load_dwordx2 v[48:49], v236, s[38:39] offset:128
	global_load_dwordx2 v[194:195], v237, s[40:41]
	global_load_dwordx2 v[50:51], v237, s[38:39]
	global_load_dwordx2 v[196:197], v237, s[40:41] offset:128
	global_load_dwordx2 v[52:53], v237, s[38:39] offset:128
	global_load_dwordx2 v[198:199], v238, s[40:41]
	global_load_dwordx2 v[78:79], v238, s[38:39]
	global_load_dwordx2 v[200:201], v238, s[40:41] offset:128
	global_load_dwordx2 v[80:81], v238, s[38:39] offset:128
	global_load_dwordx2 v[202:203], v239, s[40:41]
	global_load_dwordx2 v[82:83], v239, s[38:39]
	global_load_dwordx2 v[204:205], v239, s[40:41] offset:128
	global_load_dwordx2 v[84:85], v239, s[38:39] offset:128
	global_load_dwordx2 v[210:211], v240, s[40:41]
	global_load_dwordx2 v[110:111], v240, s[38:39]
	global_load_dwordx2 v[212:213], v240, s[40:41] offset:128
	global_load_dwordx2 v[112:113], v240, s[38:39] offset:128
	global_load_dwordx2 v[214:215], v241, s[40:41]
	global_load_dwordx2 v[114:115], v241, s[38:39]
	global_load_dwordx2 v[216:217], v241, s[40:41] offset:128
	global_load_dwordx2 v[116:117], v241, s[38:39] offset:128
	global_load_dwordx2 v[218:219], v242, s[40:41]
	global_load_dwordx2 v[142:143], v242, s[38:39]
	global_load_dwordx2 v[220:221], v242, s[40:41] offset:128
	global_load_dwordx2 v[144:145], v242, s[38:39] offset:128
	global_load_dwordx2 v[222:223], v243, s[40:41]
	global_load_dwordx2 v[146:147], v243, s[38:39]
	global_load_dwordx2 v[224:225], v243, s[40:41] offset:128
	global_load_dwordx2 v[148:149], v243, s[38:39] offset:128
	s_waitcnt vmcnt(30)
	v_cvt_f32_ubyte0_e32 v226, v46
	v_cvt_f32_ubyte1_e32 v227, v46
	v_cvt_f32_ubyte2_e32 v228, v46
	v_cvt_f32_ubyte3_e32 v229, v46
	v_cvt_f32_ubyte0_e32 v230, v47
	v_cvt_f32_ubyte1_e32 v231, v47
	v_cvt_f32_ubyte2_e32 v232, v47
	v_cvt_f32_ubyte3_e32 v233, v47
	v_cvt_f32_ubyte0_e32 v2, v190
	v_cvt_f32_ubyte1_e32 v3, v190
	v_cvt_f32_ubyte2_e32 v4, v190
	v_cvt_f32_ubyte3_e32 v5, v190
	v_cvt_f32_ubyte0_e32 v6, v191
	v_cvt_f32_ubyte1_e32 v7, v191
	v_cvt_f32_ubyte2_e32 v8, v191
	v_cvt_f32_ubyte3_e32 v9, v191
	v_rcp_iflag_f32_e32 v226, v226
	v_rcp_iflag_f32_e32 v227, v227
	v_rcp_iflag_f32_e32 v228, v228
	v_rcp_iflag_f32_e32 v229, v229
	v_rcp_iflag_f32_e32 v230, v230
	v_rcp_iflag_f32_e32 v231, v231
	v_rcp_iflag_f32_e32 v232, v232
	v_rcp_iflag_f32_e32 v233, v233
	s_nop 0
	v_pk_mul_f32 v[2:3], v[226:227], v[2:3]
	v_pk_mul_f32 v[4:5], v[228:229], v[4:5]
	v_pk_mul_f32 v[6:7], v[230:231], v[6:7]
	v_pk_mul_f32 v[8:9], v[232:233], v[8:9]
	v_pk_mul_f32 v[66:67], v[66:67], v[2:3]
	v_pk_mul_f32 v[68:69], v[68:69], v[4:5]
	v_pk_mul_f32 v[62:63], v[62:63], v[6:7]
	v_pk_mul_f32 v[64:65], v[64:65], v[8:9]
	s_waitcnt vmcnt(28)
	v_cvt_f32_ubyte0_e32 v226, v48
	v_cvt_f32_ubyte1_e32 v227, v48
	v_cvt_f32_ubyte2_e32 v228, v48
	v_cvt_f32_ubyte3_e32 v229, v48
	v_cvt_f32_ubyte0_e32 v230, v49
	v_cvt_f32_ubyte1_e32 v231, v49
	v_cvt_f32_ubyte2_e32 v232, v49
	v_cvt_f32_ubyte3_e32 v233, v49
	v_cvt_f32_ubyte0_e32 v2, v192
	v_cvt_f32_ubyte1_e32 v3, v192
	v_cvt_f32_ubyte2_e32 v4, v192
	v_cvt_f32_ubyte3_e32 v5, v192
	v_cvt_f32_ubyte0_e32 v6, v193
	v_cvt_f32_ubyte1_e32 v7, v193
	v_cvt_f32_ubyte2_e32 v8, v193
	v_cvt_f32_ubyte3_e32 v9, v193
	v_rcp_iflag_f32_e32 v226, v226
	v_rcp_iflag_f32_e32 v227, v227
	v_rcp_iflag_f32_e32 v228, v228
	v_rcp_iflag_f32_e32 v229, v229
	v_rcp_iflag_f32_e32 v230, v230
	v_rcp_iflag_f32_e32 v231, v231
	v_rcp_iflag_f32_e32 v232, v232
	v_rcp_iflag_f32_e32 v233, v233
	s_nop 0
	v_pk_mul_f32 v[2:3], v[226:227], v[2:3]
	v_pk_mul_f32 v[4:5], v[228:229], v[4:5]
	v_pk_mul_f32 v[6:7], v[230:231], v[6:7]
	v_pk_mul_f32 v[8:9], v[232:233], v[8:9]
	v_pk_mul_f32 v[170:171], v[170:171], v[2:3]
	v_pk_mul_f32 v[172:173], v[172:173], v[4:5]
	v_pk_mul_f32 v[166:167], v[166:167], v[6:7]
	v_pk_mul_f32 v[168:169], v[168:169], v[8:9]
	s_waitcnt vmcnt(26)
	v_cvt_f32_ubyte0_e32 v226, v50
	v_cvt_f32_ubyte1_e32 v227, v50
	v_cvt_f32_ubyte2_e32 v228, v50
	v_cvt_f32_ubyte3_e32 v229, v50
	v_cvt_f32_ubyte0_e32 v230, v51
	v_cvt_f32_ubyte1_e32 v231, v51
	v_cvt_f32_ubyte2_e32 v232, v51
	v_cvt_f32_ubyte3_e32 v233, v51
	v_cvt_f32_ubyte0_e32 v2, v194
	v_cvt_f32_ubyte1_e32 v3, v194
	v_cvt_f32_ubyte2_e32 v4, v194
	v_cvt_f32_ubyte3_e32 v5, v194
	v_cvt_f32_ubyte0_e32 v6, v195
	v_cvt_f32_ubyte1_e32 v7, v195
	v_cvt_f32_ubyte2_e32 v8, v195
	v_cvt_f32_ubyte3_e32 v9, v195
	v_rcp_iflag_f32_e32 v226, v226
	v_rcp_iflag_f32_e32 v227, v227
	v_rcp_iflag_f32_e32 v228, v228
	v_rcp_iflag_f32_e32 v229, v229
	v_rcp_iflag_f32_e32 v230, v230
	v_rcp_iflag_f32_e32 v231, v231
	v_rcp_iflag_f32_e32 v232, v232
	v_rcp_iflag_f32_e32 v233, v233
	s_nop 0
	v_pk_mul_f32 v[2:3], v[226:227], v[2:3]
	v_pk_mul_f32 v[4:5], v[228:229], v[4:5]
	v_pk_mul_f32 v[6:7], v[230:231], v[6:7]
	v_pk_mul_f32 v[8:9], v[232:233], v[8:9]
	v_pk_mul_f32 v[98:99], v[98:99], v[2:3]
	v_pk_mul_f32 v[100:101], v[100:101], v[4:5]
	v_pk_mul_f32 v[94:95], v[94:95], v[6:7]
	v_pk_mul_f32 v[96:97], v[96:97], v[8:9]
	s_waitcnt vmcnt(24)
; __device__ __forceinline__ float frcp(float x) { return __builtin_amdgcn_rcpf(x); }
;     static __device__ __forceinline__ float ub(unsigned w, int i) { return (float)((w >> (8 * i)) & 0xffu); }
;     __device__ __forceinline__ void chain(Acc& acc, const Unit& u, int wr, int wc, int fr, int fq) const {
;     ...
;             for (int m = 0; m < 4; ++m)
; #pragma unroll
;                 for (int bj = 0; bj < 2; ++bj) { const u32x2 gg = g[m][bj], hh = h[m][bj];
;                     float sc[8];
;                     if (sub < 2) {
; #pragma unroll
;                         for (int e = 0; e < 8; ++e) sc[e] = ub(e < 4 ? gg.x : gg.y, e & 3) * frcp(ub(e < 4 ? hh.x : hh.y, e & 3));
;                     } else {
; #pragma unroll
;                         for (int e = 0; e < 8; ++e) sc[e] = ub(e < 4 ? gg.x : gg.y, e & 3) * (1.0f / 255.0f);
;                     }
;                     f32x4 a0 = acc[ai][bj][m][0], a1 = acc[ai][bj][m][1];
;                     a0 *= (f32x4){sc[0], sc[1], sc[2], sc[3]}; a1 *= (f32x4){sc[4], sc[5], sc[6], sc[7]};
;                     if (sub < 2) { acc[ai][bj][m][0] = a0; acc[ai][bj][m][1] = a1; }
	v_cvt_f32_ubyte0_e32 v226, v52
	v_cvt_f32_ubyte1_e32 v227, v52
	v_cvt_f32_ubyte2_e32 v228, v52
	v_cvt_f32_ubyte3_e32 v229, v52
	v_cvt_f32_ubyte0_e32 v230, v53
	v_cvt_f32_ubyte1_e32 v231, v53
	v_cvt_f32_ubyte2_e32 v232, v53
	v_cvt_f32_ubyte3_e32 v233, v53
	v_cvt_f32_ubyte0_e32 v2, v196
	v_cvt_f32_ubyte1_e32 v3, v196
	v_cvt_f32_ubyte2_e32 v4, v196
	v_cvt_f32_ubyte3_e32 v5, v196
	v_cvt_f32_ubyte0_e32 v6, v197
	v_cvt_f32_ubyte1_e32 v7, v197
	v_cvt_f32_ubyte2_e32 v8, v197
	v_cvt_f32_ubyte3_e32 v9, v197
	v_rcp_iflag_f32_e32 v226, v226
	v_rcp_iflag_f32_e32 v227, v227
	v_rcp_iflag_f32_e32 v228, v228
	v_rcp_iflag_f32_e32 v229, v229
	v_rcp_iflag_f32_e32 v230, v230
	v_rcp_iflag_f32_e32 v231, v231
	v_rcp_iflag_f32_e32 v232, v232
	v_rcp_iflag_f32_e32 v233, v233
	s_nop 0
	v_pk_mul_f32 v[2:3], v[226:227], v[2:3]
	v_pk_mul_f32 v[4:5], v[228:229], v[4:5]
	v_pk_mul_f32 v[6:7], v[230:231], v[6:7]
	v_pk_mul_f32 v[8:9], v[232:233], v[8:9]
	v_pk_mul_f32 v[162:163], v[162:163], v[2:3]
	v_pk_mul_f32 v[164:165], v[164:165], v[4:5]
	v_pk_mul_f32 v[158:159], v[158:159], v[6:7]
	v_pk_mul_f32 v[160:161], v[160:161], v[8:9]
	s_waitcnt vmcnt(22)
	v_cvt_f32_ubyte0_e32 v226, v78
	v_cvt_f32_ubyte1_e32 v227, v78
	v_cvt_f32_ubyte2_e32 v228, v78
	v_cvt_f32_ubyte3_e32 v229, v78
	v_cvt_f32_ubyte0_e32 v230, v79
	v_cvt_f32_ubyte1_e32 v231, v79
	v_cvt_f32_ubyte2_e32 v232, v79
	v_cvt_f32_ubyte3_e32 v233, v79
	v_cvt_f32_ubyte0_e32 v2, v198
	v_cvt_f32_ubyte1_e32 v3, v198
	v_cvt_f32_ubyte2_e32 v4, v198
	v_cvt_f32_ubyte3_e32 v5, v198
	v_cvt_f32_ubyte0_e32 v6, v199
	v_cvt_f32_ubyte1_e32 v7, v199
	v_cvt_f32_ubyte2_e32 v8, v199
	v_cvt_f32_ubyte3_e32 v9, v199
	v_rcp_iflag_f32_e32 v226, v226
	v_rcp_iflag_f32_e32 v227, v227
	v_rcp_iflag_f32_e32 v228, v228
	v_rcp_iflag_f32_e32 v229, v229
	v_rcp_iflag_f32_e32 v230, v230
	v_rcp_iflag_f32_e32 v231, v231
	v_rcp_iflag_f32_e32 v232, v232
	v_rcp_iflag_f32_e32 v233, v233
	s_nop 0
	v_pk_mul_f32 v[2:3], v[226:227], v[2:3]
	v_pk_mul_f32 v[4:5], v[228:229], v[4:5]
	v_pk_mul_f32 v[6:7], v[230:231], v[6:7]
	v_pk_mul_f32 v[8:9], v[232:233], v[8:9]
	v_pk_mul_f32 v[130:131], v[130:131], v[2:3]
	v_pk_mul_f32 v[132:133], v[132:133], v[4:5]
	v_pk_mul_f32 v[126:127], v[126:127], v[6:7]
	v_pk_mul_f32 v[128:129], v[128:129], v[8:9]
	s_waitcnt vmcnt(20)
	v_cvt_f32_ubyte0_e32 v226, v80
	v_cvt_f32_ubyte1_e32 v227, v80
	v_cvt_f32_ubyte2_e32 v228, v80
	v_cvt_f32_ubyte3_e32 v229, v80
	v_cvt_f32_ubyte0_e32 v230, v81
	v_cvt_f32_ubyte1_e32 v231, v81
	v_cvt_f32_ubyte2_e32 v232, v81
	v_cvt_f32_ubyte3_e32 v233, v81
	v_cvt_f32_ubyte0_e32 v2, v200
	v_cvt_f32_ubyte1_e32 v3, v200
	v_cvt_f32_ubyte2_e32 v4, v200
	v_cvt_f32_ubyte3_e32 v5, v200
	v_cvt_f32_ubyte0_e32 v6, v201
	v_cvt_f32_ubyte1_e32 v7, v201
	v_cvt_f32_ubyte2_e32 v8, v201
	v_cvt_f32_ubyte3_e32 v9, v201
	v_rcp_iflag_f32_e32 v226, v226
	v_rcp_iflag_f32_e32 v227, v227
	v_rcp_iflag_f32_e32 v228, v228
	v_rcp_iflag_f32_e32 v229, v229
	v_rcp_iflag_f32_e32 v230, v230
	v_rcp_iflag_f32_e32 v231, v231
	v_rcp_iflag_f32_e32 v232, v232
	v_rcp_iflag_f32_e32 v233, v233
	s_nop 0
	v_pk_mul_f32 v[2:3], v[226:227], v[2:3]
	v_pk_mul_f32 v[4:5], v[228:229], v[4:5]
	v_pk_mul_f32 v[6:7], v[230:231], v[6:7]
	v_pk_mul_f32 v[8:9], v[232:233], v[8:9]
	v_pk_mul_f32 v[154:155], v[154:155], v[2:3]
	v_pk_mul_f32 v[156:157], v[156:157], v[4:5]
	v_pk_mul_f32 v[150:151], v[150:151], v[6:7]
	v_pk_mul_f32 v[152:153], v[152:153], v[8:9]
	s_waitcnt vmcnt(18)
	v_cvt_f32_ubyte0_e32 v226, v82
	v_cvt_f32_ubyte1_e32 v227, v82
	v_cvt_f32_ubyte2_e32 v228, v82
	v_cvt_f32_ubyte3_e32 v229, v82
	v_cvt_f32_ubyte0_e32 v230, v83
	v_cvt_f32_ubyte1_e32 v231, v83
	v_cvt_f32_ubyte2_e32 v232, v83
	v_cvt_f32_ubyte3_e32 v233, v83
	v_cvt_f32_ubyte0_e32 v2, v202
	v_cvt_f32_ubyte1_e32 v3, v202
	v_cvt_f32_ubyte2_e32 v4, v202
	v_cvt_f32_ubyte3_e32 v5, v202
	v_cvt_f32_ubyte0_e32 v6, v203
	v_cvt_f32_ubyte1_e32 v7, v203
	v_cvt_f32_ubyte2_e32 v8, v203
	v_cvt_f32_ubyte3_e32 v9, v203
	v_rcp_iflag_f32_e32 v226, v226
	v_rcp_iflag_f32_e32 v227, v227
	v_rcp_iflag_f32_e32 v228, v228
	v_rcp_iflag_f32_e32 v229, v229
	v_rcp_iflag_f32_e32 v230, v230
	v_rcp_iflag_f32_e32 v231, v231
	v_rcp_iflag_f32_e32 v232, v232
	v_rcp_iflag_f32_e32 v233, v233
	s_nop 0
	v_pk_mul_f32 v[2:3], v[226:227], v[2:3]
	v_pk_mul_f32 v[4:5], v[228:229], v[4:5]
	v_pk_mul_f32 v[6:7], v[230:231], v[6:7]
	v_pk_mul_f32 v[8:9], v[232:233], v[8:9]
	v_pk_mul_f32 v[138:139], v[138:139], v[2:3]
	v_pk_mul_f32 v[140:141], v[140:141], v[4:5]
	v_pk_mul_f32 v[134:135], v[134:135], v[6:7]
	v_pk_mul_f32 v[136:137], v[136:137], v[8:9]
	s_waitcnt vmcnt(16)
	v_cvt_f32_ubyte0_e32 v226, v84
	v_cvt_f32_ubyte1_e32 v227, v84
	v_cvt_f32_ubyte2_e32 v228, v84
	v_cvt_f32_ubyte3_e32 v229, v84
	v_cvt_f32_ubyte0_e32 v230, v85
	v_cvt_f32_ubyte1_e32 v231, v85
	v_cvt_f32_ubyte2_e32 v232, v85
	v_cvt_f32_ubyte3_e32 v233, v85
	v_cvt_f32_ubyte0_e32 v2, v204
	v_cvt_f32_ubyte1_e32 v3, v204
	v_cvt_f32_ubyte2_e32 v4, v204
	v_cvt_f32_ubyte3_e32 v5, v204
	v_cvt_f32_ubyte0_e32 v6, v205
	v_cvt_f32_ubyte1_e32 v7, v205
	v_cvt_f32_ubyte2_e32 v8, v205
	v_cvt_f32_ubyte3_e32 v9, v205
	v_rcp_iflag_f32_e32 v226, v226
	v_rcp_iflag_f32_e32 v227, v227
	v_rcp_iflag_f32_e32 v228, v228
	v_rcp_iflag_f32_e32 v229, v229
	v_rcp_iflag_f32_e32 v230, v230
	v_rcp_iflag_f32_e32 v231, v231
	v_rcp_iflag_f32_e32 v232, v232
	v_rcp_iflag_f32_e32 v233, v233
	s_nop 0
	v_pk_mul_f32 v[2:3], v[226:227], v[2:3]
	v_pk_mul_f32 v[4:5], v[228:229], v[4:5]
	v_pk_mul_f32 v[6:7], v[230:231], v[6:7]
	v_pk_mul_f32 v[8:9], v[232:233], v[8:9]
	v_pk_mul_f32 v[122:123], v[122:123], v[2:3]
	v_pk_mul_f32 v[124:125], v[124:125], v[4:5]
	v_pk_mul_f32 v[118:119], v[118:119], v[6:7]
	v_pk_mul_f32 v[120:121], v[120:121], v[8:9]
	s_waitcnt vmcnt(14)
; __device__ __forceinline__ float frcp(float x) { return __builtin_amdgcn_rcpf(x); }
;     static __device__ __forceinline__ float ub(unsigned w, int i) { return (float)((w >> (8 * i)) & 0xffu); }
;     __device__ __forceinline__ void chain(Acc& acc, const Unit& u, int wr, int wc, int fr, int fq) const {
;     ...
;             for (int m = 0; m < 4; ++m)
; #pragma unroll
;                 for (int bj = 0; bj < 2; ++bj) { const u32x2 gg = g[m][bj], hh = h[m][bj];
;                     float sc[8];
;                     if (sub < 2) {
; #pragma unroll
;                         for (int e = 0; e < 8; ++e) sc[e] = ub(e < 4 ? gg.x : gg.y, e & 3) * frcp(ub(e < 4 ? hh.x : hh.y, e & 3));
;                     } else {
; #pragma unroll
;                         for (int e = 0; e < 8; ++e) sc[e] = ub(e < 4 ? gg.x : gg.y, e & 3) * (1.0f / 255.0f);
;                     }
;                     f32x4 a0 = acc[ai][bj][m][0], a1 = acc[ai][bj][m][1];
;                     a0 *= (f32x4){sc[0], sc[1], sc[2], sc[3]}; a1 *= (f32x4){sc[4], sc[5], sc[6], sc[7]};
;                     if (sub < 2) { acc[ai][bj][m][0] = a0; acc[ai][bj][m][1] = a1; }
	v_cvt_f32_ubyte0_e32 v226, v110
	v_cvt_f32_ubyte1_e32 v227, v110
	v_cvt_f32_ubyte2_e32 v228, v110
	v_cvt_f32_ubyte3_e32 v229, v110
	v_cvt_f32_ubyte0_e32 v230, v111
	v_cvt_f32_ubyte1_e32 v231, v111
	v_cvt_f32_ubyte2_e32 v232, v111
	v_cvt_f32_ubyte3_e32 v233, v111
	v_cvt_f32_ubyte0_e32 v2, v210
	v_cvt_f32_ubyte1_e32 v3, v210
	v_cvt_f32_ubyte2_e32 v4, v210
	v_cvt_f32_ubyte3_e32 v5, v210
	v_cvt_f32_ubyte0_e32 v6, v211
	v_cvt_f32_ubyte1_e32 v7, v211
	v_cvt_f32_ubyte2_e32 v8, v211
	v_cvt_f32_ubyte3_e32 v9, v211
	v_rcp_iflag_f32_e32 v226, v226
	v_rcp_iflag_f32_e32 v227, v227
	v_rcp_iflag_f32_e32 v228, v228
	v_rcp_iflag_f32_e32 v229, v229
	v_rcp_iflag_f32_e32 v230, v230
	v_rcp_iflag_f32_e32 v231, v231
	v_rcp_iflag_f32_e32 v232, v232
	v_rcp_iflag_f32_e32 v233, v233
	s_nop 0
	v_pk_mul_f32 v[2:3], v[226:227], v[2:3]
	v_pk_mul_f32 v[4:5], v[228:229], v[4:5]
	v_pk_mul_f32 v[6:7], v[230:231], v[6:7]
	v_pk_mul_f32 v[8:9], v[232:233], v[8:9]
	v_pk_mul_f32 v[106:107], v[106:107], v[2:3]
	v_pk_mul_f32 v[108:109], v[108:109], v[4:5]
	v_pk_mul_f32 v[102:103], v[102:103], v[6:7]
	v_pk_mul_f32 v[104:105], v[104:105], v[8:9]
	s_waitcnt vmcnt(12)
	v_cvt_f32_ubyte0_e32 v226, v112
	v_cvt_f32_ubyte1_e32 v227, v112
	v_cvt_f32_ubyte2_e32 v228, v112
	v_cvt_f32_ubyte3_e32 v229, v112
	v_cvt_f32_ubyte0_e32 v230, v113
	v_cvt_f32_ubyte1_e32 v231, v113
	v_cvt_f32_ubyte2_e32 v232, v113
	v_cvt_f32_ubyte3_e32 v233, v113
	v_cvt_f32_ubyte0_e32 v2, v212
	v_cvt_f32_ubyte1_e32 v3, v212
	v_cvt_f32_ubyte2_e32 v4, v212
	v_cvt_f32_ubyte3_e32 v5, v212
	v_cvt_f32_ubyte0_e32 v6, v213
	v_cvt_f32_ubyte1_e32 v7, v213
	v_cvt_f32_ubyte2_e32 v8, v213
	v_cvt_f32_ubyte3_e32 v9, v213
	v_rcp_iflag_f32_e32 v226, v226
	v_rcp_iflag_f32_e32 v227, v227
	v_rcp_iflag_f32_e32 v228, v228
	v_rcp_iflag_f32_e32 v229, v229
	v_rcp_iflag_f32_e32 v230, v230
	v_rcp_iflag_f32_e32 v231, v231
	v_rcp_iflag_f32_e32 v232, v232
	v_rcp_iflag_f32_e32 v233, v233
	s_nop 0
	v_pk_mul_f32 v[2:3], v[226:227], v[2:3]
	v_pk_mul_f32 v[4:5], v[228:229], v[4:5]
	v_pk_mul_f32 v[6:7], v[230:231], v[6:7]
	v_pk_mul_f32 v[8:9], v[232:233], v[8:9]
	v_pk_mul_f32 v[90:91], v[90:91], v[2:3]
	v_pk_mul_f32 v[92:93], v[92:93], v[4:5]
	v_pk_mul_f32 v[86:87], v[86:87], v[6:7]
	v_pk_mul_f32 v[88:89], v[88:89], v[8:9]
	s_waitcnt vmcnt(10)
	v_cvt_f32_ubyte0_e32 v226, v114
	v_cvt_f32_ubyte1_e32 v227, v114
	v_cvt_f32_ubyte2_e32 v228, v114
	v_cvt_f32_ubyte3_e32 v229, v114
	v_cvt_f32_ubyte0_e32 v230, v115
	v_cvt_f32_ubyte1_e32 v231, v115
	v_cvt_f32_ubyte2_e32 v232, v115
	v_cvt_f32_ubyte3_e32 v233, v115
	v_cvt_f32_ubyte0_e32 v2, v214
	v_cvt_f32_ubyte1_e32 v3, v214
	v_cvt_f32_ubyte2_e32 v4, v214
	v_cvt_f32_ubyte3_e32 v5, v214
	v_cvt_f32_ubyte0_e32 v6, v215
	v_cvt_f32_ubyte1_e32 v7, v215
	v_cvt_f32_ubyte2_e32 v8, v215
	v_cvt_f32_ubyte3_e32 v9, v215
	v_rcp_iflag_f32_e32 v226, v226
	v_rcp_iflag_f32_e32 v227, v227
	v_rcp_iflag_f32_e32 v228, v228
	v_rcp_iflag_f32_e32 v229, v229
	v_rcp_iflag_f32_e32 v230, v230
	v_rcp_iflag_f32_e32 v231, v231
	v_rcp_iflag_f32_e32 v232, v232
	v_rcp_iflag_f32_e32 v233, v233
	s_nop 0
	v_pk_mul_f32 v[2:3], v[226:227], v[2:3]
	v_pk_mul_f32 v[4:5], v[228:229], v[4:5]
	v_pk_mul_f32 v[6:7], v[230:231], v[6:7]
	v_pk_mul_f32 v[8:9], v[232:233], v[8:9]
	v_pk_mul_f32 v[74:75], v[74:75], v[2:3]
	v_pk_mul_f32 v[76:77], v[76:77], v[4:5]
	v_pk_mul_f32 v[70:71], v[70:71], v[6:7]
	v_pk_mul_f32 v[72:73], v[72:73], v[8:9]
	s_waitcnt vmcnt(8)
	v_cvt_f32_ubyte0_e32 v226, v116
	v_cvt_f32_ubyte1_e32 v227, v116
	v_cvt_f32_ubyte2_e32 v228, v116
	v_cvt_f32_ubyte3_e32 v229, v116
	v_cvt_f32_ubyte0_e32 v230, v117
	v_cvt_f32_ubyte1_e32 v231, v117
	v_cvt_f32_ubyte2_e32 v232, v117
	v_cvt_f32_ubyte3_e32 v233, v117
	v_cvt_f32_ubyte0_e32 v2, v216
	v_cvt_f32_ubyte1_e32 v3, v216
	v_cvt_f32_ubyte2_e32 v4, v216
	v_cvt_f32_ubyte3_e32 v5, v216
	v_cvt_f32_ubyte0_e32 v6, v217
	v_cvt_f32_ubyte1_e32 v7, v217
	v_cvt_f32_ubyte2_e32 v8, v217
	v_cvt_f32_ubyte3_e32 v9, v217
	v_rcp_iflag_f32_e32 v226, v226
	v_rcp_iflag_f32_e32 v227, v227
	v_rcp_iflag_f32_e32 v228, v228
	v_rcp_iflag_f32_e32 v229, v229
	v_rcp_iflag_f32_e32 v230, v230
	v_rcp_iflag_f32_e32 v231, v231
	v_rcp_iflag_f32_e32 v232, v232
	v_rcp_iflag_f32_e32 v233, v233
	s_nop 0
	v_pk_mul_f32 v[2:3], v[226:227], v[2:3]
	v_pk_mul_f32 v[4:5], v[228:229], v[4:5]
	v_pk_mul_f32 v[6:7], v[230:231], v[6:7]
	v_pk_mul_f32 v[8:9], v[232:233], v[8:9]
	v_pk_mul_f32 v[58:59], v[58:59], v[2:3]
	v_pk_mul_f32 v[60:61], v[60:61], v[4:5]
	v_pk_mul_f32 v[54:55], v[54:55], v[6:7]
	v_pk_mul_f32 v[56:57], v[56:57], v[8:9]
	s_waitcnt vmcnt(6)
	v_cvt_f32_ubyte0_e32 v226, v142
	v_cvt_f32_ubyte1_e32 v227, v142
	v_cvt_f32_ubyte2_e32 v228, v142
	v_cvt_f32_ubyte3_e32 v229, v142
	v_cvt_f32_ubyte0_e32 v230, v143
	v_cvt_f32_ubyte1_e32 v231, v143
	v_cvt_f32_ubyte2_e32 v232, v143
	v_cvt_f32_ubyte3_e32 v233, v143
	v_cvt_f32_ubyte0_e32 v2, v218
	v_cvt_f32_ubyte1_e32 v3, v218
	v_cvt_f32_ubyte2_e32 v4, v218
	v_cvt_f32_ubyte3_e32 v5, v218
	v_cvt_f32_ubyte0_e32 v6, v219
	v_cvt_f32_ubyte1_e32 v7, v219
	v_cvt_f32_ubyte2_e32 v8, v219
	v_cvt_f32_ubyte3_e32 v9, v219
	v_rcp_iflag_f32_e32 v226, v226
	v_rcp_iflag_f32_e32 v227, v227
	v_rcp_iflag_f32_e32 v228, v228
	v_rcp_iflag_f32_e32 v229, v229
	v_rcp_iflag_f32_e32 v230, v230
	v_rcp_iflag_f32_e32 v231, v231
	v_rcp_iflag_f32_e32 v232, v232
	v_rcp_iflag_f32_e32 v233, v233
	s_nop 0
	v_pk_mul_f32 v[2:3], v[226:227], v[2:3]
	v_pk_mul_f32 v[4:5], v[228:229], v[4:5]
	v_pk_mul_f32 v[6:7], v[230:231], v[6:7]
	v_pk_mul_f32 v[8:9], v[232:233], v[8:9]
	v_pk_mul_f32 v[42:43], v[42:43], v[2:3]
	v_pk_mul_f32 v[44:45], v[44:45], v[4:5]
	v_pk_mul_f32 v[38:39], v[38:39], v[6:7]
	v_pk_mul_f32 v[40:41], v[40:41], v[8:9]
	s_waitcnt vmcnt(4)
; __device__ __forceinline__ unsigned pk2(float lo, float hi) { f32x2 v = {lo, hi}; bf16x2_t b = __builtin_convertvector(v, bf16x2_t); return __builtin_bit_cast(unsigned, b); }
; __device__ __forceinline__ float frcp(float x) { return __builtin_amdgcn_rcpf(x); }
;     static __device__ __forceinline__ float ub(unsigned w, int i) { return (float)((w >> (8 * i)) & 0xffu); }
;     __device__ __forceinline__ void chain(Acc& acc, const Unit& u, int wr, int wc, int fr, int fq) const {
;     ...
;                 for (int bj = 0; bj < 2; ++bj) { const unsigned char* p = GT + (size_t)(row0 + ai * HALF + m * 16) * NGT + col0 + bj * HALF;
;                     g[m][bj] = *(const u32x2*)(p + sub * DM); h[m][bj] = *(const u32x2*)(p + subn * DM); }
; #pragma unroll
;             for (int m = 0; m < 4; ++m)
; #pragma unroll
;                 for (int bj = 0; bj < 2; ++bj) { const u32x2 gg = g[m][bj], hh = h[m][bj];
;                     float sc[8];
;                     if (sub < 2) {
; #pragma unroll
;                         for (int e = 0; e < 8; ++e) sc[e] = ub(e < 4 ? gg.x : gg.y, e & 3) * frcp(ub(e < 4 ? hh.x : hh.y, e & 3));
;                     } else {
; #pragma unroll
;                         for (int e = 0; e < 8; ++e) sc[e] = ub(e < 4 ? gg.x : gg.y, e & 3) * (1.0f / 255.0f);
;                     }
;                     f32x4 a0 = acc[ai][bj][m][0], a1 = acc[ai][bj][m][1];
;                     a0 *= (f32x4){sc[0], sc[1], sc[2], sc[3]}; a1 *= (f32x4){sc[4], sc[5], sc[6], sc[7]};
;                     if (sub < 2) { acc[ai][bj][m][0] = a0; acc[ai][bj][m][1] = a1; }
;                     else { u32x4 w; w.x = pk2(a0[0], a0[1]); w.y = pk2(a0[2], a0[3]); w.z = pk2(a1[0], a1[1]); w.w = pk2(a1[2], a1[3]);
;                         *(u32x4*)(MERGED + (size_t)(row0 + ai * HALF + m * 16) * DM + col0 + bj * HALF) = w; } }
	v_cvt_f32_ubyte0_e32 v226, v144
	v_cvt_f32_ubyte1_e32 v227, v144
	v_cvt_f32_ubyte2_e32 v228, v144
	v_cvt_f32_ubyte3_e32 v229, v144
	v_cvt_f32_ubyte0_e32 v230, v145
	v_cvt_f32_ubyte1_e32 v231, v145
	v_cvt_f32_ubyte2_e32 v232, v145
	v_cvt_f32_ubyte3_e32 v233, v145
	v_cvt_f32_ubyte0_e32 v2, v220
	v_cvt_f32_ubyte1_e32 v3, v220
	v_cvt_f32_ubyte2_e32 v4, v220
	v_cvt_f32_ubyte3_e32 v5, v220
	v_cvt_f32_ubyte0_e32 v6, v221
	v_cvt_f32_ubyte1_e32 v7, v221
	v_cvt_f32_ubyte2_e32 v8, v221
	v_cvt_f32_ubyte3_e32 v9, v221
	v_rcp_iflag_f32_e32 v226, v226
	v_rcp_iflag_f32_e32 v227, v227
	v_rcp_iflag_f32_e32 v228, v228
	v_rcp_iflag_f32_e32 v229, v229
	v_rcp_iflag_f32_e32 v230, v230
	v_rcp_iflag_f32_e32 v231, v231
	v_rcp_iflag_f32_e32 v232, v232
	v_rcp_iflag_f32_e32 v233, v233
	s_nop 0
	v_pk_mul_f32 v[2:3], v[226:227], v[2:3]
	v_pk_mul_f32 v[4:5], v[228:229], v[4:5]
	v_pk_mul_f32 v[6:7], v[230:231], v[6:7]
	v_pk_mul_f32 v[8:9], v[232:233], v[8:9]
	v_pk_mul_f32 v[34:35], v[34:35], v[2:3]
	v_pk_mul_f32 v[36:37], v[36:37], v[4:5]
	v_pk_mul_f32 v[30:31], v[30:31], v[6:7]
	v_pk_mul_f32 v[32:33], v[32:33], v[8:9]
	s_waitcnt vmcnt(2)
	v_cvt_f32_ubyte0_e32 v226, v146
	v_cvt_f32_ubyte1_e32 v227, v146
	v_cvt_f32_ubyte2_e32 v228, v146
	v_cvt_f32_ubyte3_e32 v229, v146
	v_cvt_f32_ubyte0_e32 v230, v147
	v_cvt_f32_ubyte1_e32 v231, v147
	v_cvt_f32_ubyte2_e32 v232, v147
	v_cvt_f32_ubyte3_e32 v233, v147
	v_cvt_f32_ubyte0_e32 v2, v222
	v_cvt_f32_ubyte1_e32 v3, v222
	v_cvt_f32_ubyte2_e32 v4, v222
	v_cvt_f32_ubyte3_e32 v5, v222
	v_cvt_f32_ubyte0_e32 v6, v223
	v_cvt_f32_ubyte1_e32 v7, v223
	v_cvt_f32_ubyte2_e32 v8, v223
	v_cvt_f32_ubyte3_e32 v9, v223
	v_rcp_iflag_f32_e32 v226, v226
	v_rcp_iflag_f32_e32 v227, v227
	v_rcp_iflag_f32_e32 v228, v228
	v_rcp_iflag_f32_e32 v229, v229
	v_rcp_iflag_f32_e32 v230, v230
	v_rcp_iflag_f32_e32 v231, v231
	v_rcp_iflag_f32_e32 v232, v232
	v_rcp_iflag_f32_e32 v233, v233
	s_nop 0
	v_pk_mul_f32 v[2:3], v[226:227], v[2:3]
	v_pk_mul_f32 v[4:5], v[228:229], v[4:5]
	v_pk_mul_f32 v[6:7], v[230:231], v[6:7]
	v_pk_mul_f32 v[8:9], v[232:233], v[8:9]
	v_pk_mul_f32 v[26:27], v[26:27], v[2:3]
	v_pk_mul_f32 v[28:29], v[28:29], v[4:5]
	v_pk_mul_f32 v[22:23], v[22:23], v[6:7]
	v_pk_mul_f32 v[24:25], v[24:25], v[8:9]
	s_waitcnt vmcnt(0)
	v_cvt_f32_ubyte0_e32 v226, v148
	v_cvt_f32_ubyte1_e32 v227, v148
	v_cvt_f32_ubyte2_e32 v228, v148
	v_cvt_f32_ubyte3_e32 v229, v148
	v_cvt_f32_ubyte0_e32 v230, v149
	v_cvt_f32_ubyte1_e32 v231, v149
	v_cvt_f32_ubyte2_e32 v232, v149
	v_cvt_f32_ubyte3_e32 v233, v149
	v_cvt_f32_ubyte0_e32 v2, v224
	v_cvt_f32_ubyte1_e32 v3, v224
	v_cvt_f32_ubyte2_e32 v4, v224
	v_cvt_f32_ubyte3_e32 v5, v224
	v_cvt_f32_ubyte0_e32 v6, v225
	v_cvt_f32_ubyte1_e32 v7, v225
	v_cvt_f32_ubyte2_e32 v8, v225
	v_cvt_f32_ubyte3_e32 v9, v225
	v_rcp_iflag_f32_e32 v226, v226
	v_rcp_iflag_f32_e32 v227, v227
	v_rcp_iflag_f32_e32 v228, v228
	v_rcp_iflag_f32_e32 v229, v229
	v_rcp_iflag_f32_e32 v230, v230
	v_rcp_iflag_f32_e32 v231, v231
	v_rcp_iflag_f32_e32 v232, v232
	v_rcp_iflag_f32_e32 v233, v233
	s_nop 0
	v_pk_mul_f32 v[2:3], v[226:227], v[2:3]
	v_pk_mul_f32 v[4:5], v[228:229], v[4:5]
	v_pk_mul_f32 v[6:7], v[230:231], v[6:7]
	v_pk_mul_f32 v[8:9], v[232:233], v[8:9]
	v_pk_mul_f32 v[18:19], v[18:19], v[2:3]
	v_pk_mul_f32 v[20:21], v[20:21], v[4:5]
	v_pk_mul_f32 v[14:15], v[14:15], v[6:7]
	v_pk_mul_f32 v[16:17], v[16:17], v[8:9]
	s_branch .Lp3c_done
.Lp3c_last:
	global_load_dwordx2 v[190:191], v236, s[40:41]
	global_load_dwordx2 v[192:193], v236, s[40:41] offset:128
	global_load_dwordx2 v[194:195], v237, s[40:41]
	global_load_dwordx2 v[196:197], v237, s[40:41] offset:128
	global_load_dwordx2 v[198:199], v238, s[40:41]
	global_load_dwordx2 v[200:201], v238, s[40:41] offset:128
	global_load_dwordx2 v[202:203], v239, s[40:41]
	global_load_dwordx2 v[204:205], v239, s[40:41] offset:128
	global_load_dwordx2 v[210:211], v240, s[40:41]
	global_load_dwordx2 v[212:213], v240, s[40:41] offset:128
	global_load_dwordx2 v[214:215], v241, s[40:41]
	global_load_dwordx2 v[216:217], v241, s[40:41] offset:128
	global_load_dwordx2 v[218:219], v242, s[40:41]
	global_load_dwordx2 v[220:221], v242, s[40:41] offset:128
	global_load_dwordx2 v[222:223], v243, s[40:41]
	global_load_dwordx2 v[224:225], v243, s[40:41] offset:128
	v_lshlrev_b32_e32 v235, 1, v235
	v_lshl_add_u32 v244, v234, 12, v235
	v_add_u32_e32 v245, 0x10000, v244
	v_add_u32_e32 v246, 0x20000, v244
	v_add_u32_e32 v247, 0x30000, v244
	v_add_u32_e32 v248, 0x80000, v244
	v_add_u32_e32 v249, 0x90000, v244
	v_add_u32_e32 v250, 0xa0000, v244
	v_add_u32_e32 v251, 0xb0000, v244
	s_waitcnt vmcnt(15)
	v_cvt_f32_ubyte0_e32 v2, v190
	v_cvt_f32_ubyte1_e32 v3, v190
	v_cvt_f32_ubyte2_e32 v4, v190
	v_cvt_f32_ubyte3_e32 v5, v190
	v_cvt_f32_ubyte0_e32 v6, v191
	v_cvt_f32_ubyte1_e32 v7, v191
	v_cvt_f32_ubyte2_e32 v8, v191
	v_cvt_f32_ubyte3_e32 v9, v191
	v_pk_mul_f32 v[2:3], v[2:3], s[22:23] op_sel_hi:[1,0]
	v_pk_mul_f32 v[4:5], v[4:5], s[22:23] op_sel_hi:[1,0]
	v_pk_mul_f32 v[6:7], v[6:7], s[22:23] op_sel_hi:[1,0]
	v_pk_mul_f32 v[8:9], v[8:9], s[22:23] op_sel_hi:[1,0]
	v_pk_mul_f32 v[2:3], v[66:67], v[2:3]
	v_pk_mul_f32 v[4:5], v[68:69], v[4:5]
	v_pk_mul_f32 v[6:7], v[62:63], v[6:7]
	v_pk_mul_f32 v[8:9], v[64:65], v[8:9]
	v_cvt_pk_bf16_f32 v226, v2, v3
	v_cvt_pk_bf16_f32 v227, v4, v5
	v_cvt_pk_bf16_f32 v228, v6, v7
	v_cvt_pk_bf16_f32 v229, v8, v9
	global_store_dwordx4 v244, v[226:229], s[16:17]
	s_waitcnt vmcnt(15)
; __device__ __forceinline__ unsigned pk2(float lo, float hi) { f32x2 v = {lo, hi}; bf16x2_t b = __builtin_convertvector(v, bf16x2_t); return __builtin_bit_cast(unsigned, b); }
;     static __device__ __forceinline__ float ub(unsigned w, int i) { return (float)((w >> (8 * i)) & 0xffu); }
;     __device__ __forceinline__ void chain(Acc& acc, const Unit& u, int wr, int wc, int fr, int fq) const {
;     ...
; #pragma unroll
;                         for (int e = 0; e < 8; ++e) sc[e] = ub(e < 4 ? gg.x : gg.y, e & 3) * (1.0f / 255.0f);
;                     }
;                     f32x4 a0 = acc[ai][bj][m][0], a1 = acc[ai][bj][m][1];
;                     a0 *= (f32x4){sc[0], sc[1], sc[2], sc[3]}; a1 *= (f32x4){sc[4], sc[5], sc[6], sc[7]};
;                     if (sub < 2) { acc[ai][bj][m][0] = a0; acc[ai][bj][m][1] = a1; }
;                     else { u32x4 w; w.x = pk2(a0[0], a0[1]); w.y = pk2(a0[2], a0[3]); w.z = pk2(a1[0], a1[1]); w.w = pk2(a1[2], a1[3]);
;                         *(u32x4*)(MERGED + (size_t)(row0 + ai * HALF + m * 16) * DM + col0 + bj * HALF) = w; } }
	v_cvt_f32_ubyte0_e32 v2, v192
	v_cvt_f32_ubyte1_e32 v3, v192
	v_cvt_f32_ubyte2_e32 v4, v192
	v_cvt_f32_ubyte3_e32 v5, v192
	v_cvt_f32_ubyte0_e32 v6, v193
	v_cvt_f32_ubyte1_e32 v7, v193
	v_cvt_f32_ubyte2_e32 v8, v193
	v_cvt_f32_ubyte3_e32 v9, v193
	v_pk_mul_f32 v[2:3], v[2:3], s[22:23] op_sel_hi:[1,0]
	v_pk_mul_f32 v[4:5], v[4:5], s[22:23] op_sel_hi:[1,0]
	v_pk_mul_f32 v[6:7], v[6:7], s[22:23] op_sel_hi:[1,0]
	v_pk_mul_f32 v[8:9], v[8:9], s[22:23] op_sel_hi:[1,0]
	v_pk_mul_f32 v[2:3], v[170:171], v[2:3]
	v_pk_mul_f32 v[4:5], v[172:173], v[4:5]
	v_pk_mul_f32 v[6:7], v[166:167], v[6:7]
	v_pk_mul_f32 v[8:9], v[168:169], v[8:9]
	v_cvt_pk_bf16_f32 v230, v2, v3
	v_cvt_pk_bf16_f32 v231, v4, v5
	v_cvt_pk_bf16_f32 v232, v6, v7
	v_cvt_pk_bf16_f32 v233, v8, v9
	global_store_dwordx4 v244, v[230:233], s[16:17] offset:256
	s_waitcnt vmcnt(15)
	v_cvt_f32_ubyte0_e32 v2, v194
	v_cvt_f32_ubyte1_e32 v3, v194
	v_cvt_f32_ubyte2_e32 v4, v194
	v_cvt_f32_ubyte3_e32 v5, v194
	v_cvt_f32_ubyte0_e32 v6, v195
	v_cvt_f32_ubyte1_e32 v7, v195
	v_cvt_f32_ubyte2_e32 v8, v195
	v_cvt_f32_ubyte3_e32 v9, v195
	v_pk_mul_f32 v[2:3], v[2:3], s[22:23] op_sel_hi:[1,0]
	v_pk_mul_f32 v[4:5], v[4:5], s[22:23] op_sel_hi:[1,0]
	v_pk_mul_f32 v[6:7], v[6:7], s[22:23] op_sel_hi:[1,0]
	v_pk_mul_f32 v[8:9], v[8:9], s[22:23] op_sel_hi:[1,0]
	v_pk_mul_f32 v[2:3], v[98:99], v[2:3]
	v_pk_mul_f32 v[4:5], v[100:101], v[4:5]
	v_pk_mul_f32 v[6:7], v[94:95], v[6:7]
	v_pk_mul_f32 v[8:9], v[96:97], v[8:9]
	v_cvt_pk_bf16_f32 v226, v2, v3
	v_cvt_pk_bf16_f32 v227, v4, v5
	v_cvt_pk_bf16_f32 v228, v6, v7
	v_cvt_pk_bf16_f32 v229, v8, v9
	global_store_dwordx4 v245, v[226:229], s[16:17]
	s_waitcnt vmcnt(15)
	v_cvt_f32_ubyte0_e32 v2, v196
	v_cvt_f32_ubyte1_e32 v3, v196
	v_cvt_f32_ubyte2_e32 v4, v196
	v_cvt_f32_ubyte3_e32 v5, v196
	v_cvt_f32_ubyte0_e32 v6, v197
	v_cvt_f32_ubyte1_e32 v7, v197
	v_cvt_f32_ubyte2_e32 v8, v197
	v_cvt_f32_ubyte3_e32 v9, v197
	v_pk_mul_f32 v[2:3], v[2:3], s[22:23] op_sel_hi:[1,0]
	v_pk_mul_f32 v[4:5], v[4:5], s[22:23] op_sel_hi:[1,0]
	v_pk_mul_f32 v[6:7], v[6:7], s[22:23] op_sel_hi:[1,0]
	v_pk_mul_f32 v[8:9], v[8:9], s[22:23] op_sel_hi:[1,0]
	v_pk_mul_f32 v[2:3], v[162:163], v[2:3]
	v_pk_mul_f32 v[4:5], v[164:165], v[4:5]
	v_pk_mul_f32 v[6:7], v[158:159], v[6:7]
	v_pk_mul_f32 v[8:9], v[160:161], v[8:9]
	v_cvt_pk_bf16_f32 v230, v2, v3
	v_cvt_pk_bf16_f32 v231, v4, v5
	v_cvt_pk_bf16_f32 v232, v6, v7
	v_cvt_pk_bf16_f32 v233, v8, v9
	global_store_dwordx4 v245, v[230:233], s[16:17] offset:256
	s_waitcnt vmcnt(15)
	v_cvt_f32_ubyte0_e32 v2, v198
	v_cvt_f32_ubyte1_e32 v3, v198
	v_cvt_f32_ubyte2_e32 v4, v198
	v_cvt_f32_ubyte3_e32 v5, v198
	v_cvt_f32_ubyte0_e32 v6, v199
	v_cvt_f32_ubyte1_e32 v7, v199
	v_cvt_f32_ubyte2_e32 v8, v199
	v_cvt_f32_ubyte3_e32 v9, v199
	v_pk_mul_f32 v[2:3], v[2:3], s[22:23] op_sel_hi:[1,0]
	v_pk_mul_f32 v[4:5], v[4:5], s[22:23] op_sel_hi:[1,0]
	v_pk_mul_f32 v[6:7], v[6:7], s[22:23] op_sel_hi:[1,0]
	v_pk_mul_f32 v[8:9], v[8:9], s[22:23] op_sel_hi:[1,0]
	v_pk_mul_f32 v[2:3], v[130:131], v[2:3]
	v_pk_mul_f32 v[4:5], v[132:133], v[4:5]
	v_pk_mul_f32 v[6:7], v[126:127], v[6:7]
	v_pk_mul_f32 v[8:9], v[128:129], v[8:9]
	v_cvt_pk_bf16_f32 v226, v2, v3
	v_cvt_pk_bf16_f32 v227, v4, v5
	v_cvt_pk_bf16_f32 v228, v6, v7
	v_cvt_pk_bf16_f32 v229, v8, v9
	global_store_dwordx4 v246, v[226:229], s[16:17]
	s_waitcnt vmcnt(15)
	v_cvt_f32_ubyte0_e32 v2, v200
	v_cvt_f32_ubyte1_e32 v3, v200
	v_cvt_f32_ubyte2_e32 v4, v200
	v_cvt_f32_ubyte3_e32 v5, v200
	v_cvt_f32_ubyte0_e32 v6, v201
	v_cvt_f32_ubyte1_e32 v7, v201
	v_cvt_f32_ubyte2_e32 v8, v201
	v_cvt_f32_ubyte3_e32 v9, v201
	v_pk_mul_f32 v[2:3], v[2:3], s[22:23] op_sel_hi:[1,0]
	v_pk_mul_f32 v[4:5], v[4:5], s[22:23] op_sel_hi:[1,0]
	v_pk_mul_f32 v[6:7], v[6:7], s[22:23] op_sel_hi:[1,0]
	v_pk_mul_f32 v[8:9], v[8:9], s[22:23] op_sel_hi:[1,0]
	v_pk_mul_f32 v[2:3], v[154:155], v[2:3]
	v_pk_mul_f32 v[4:5], v[156:157], v[4:5]
	v_pk_mul_f32 v[6:7], v[150:151], v[6:7]
	v_pk_mul_f32 v[8:9], v[152:153], v[8:9]
	v_cvt_pk_bf16_f32 v230, v2, v3
	v_cvt_pk_bf16_f32 v231, v4, v5
	v_cvt_pk_bf16_f32 v232, v6, v7
	v_cvt_pk_bf16_f32 v233, v8, v9
	global_store_dwordx4 v246, v[230:233], s[16:17] offset:256
	s_waitcnt vmcnt(15)
	v_cvt_f32_ubyte0_e32 v2, v202
	v_cvt_f32_ubyte1_e32 v3, v202
	v_cvt_f32_ubyte2_e32 v4, v202
	v_cvt_f32_ubyte3_e32 v5, v202
	v_cvt_f32_ubyte0_e32 v6, v203
	v_cvt_f32_ubyte1_e32 v7, v203
	v_cvt_f32_ubyte2_e32 v8, v203
	v_cvt_f32_ubyte3_e32 v9, v203
	v_pk_mul_f32 v[2:3], v[2:3], s[22:23] op_sel_hi:[1,0]
	v_pk_mul_f32 v[4:5], v[4:5], s[22:23] op_sel_hi:[1,0]
	v_pk_mul_f32 v[6:7], v[6:7], s[22:23] op_sel_hi:[1,0]
	v_pk_mul_f32 v[8:9], v[8:9], s[22:23] op_sel_hi:[1,0]
	v_pk_mul_f32 v[2:3], v[138:139], v[2:3]
	v_pk_mul_f32 v[4:5], v[140:141], v[4:5]
	v_pk_mul_f32 v[6:7], v[134:135], v[6:7]
	v_pk_mul_f32 v[8:9], v[136:137], v[8:9]
	v_cvt_pk_bf16_f32 v226, v2, v3
	v_cvt_pk_bf16_f32 v227, v4, v5
	v_cvt_pk_bf16_f32 v228, v6, v7
	v_cvt_pk_bf16_f32 v229, v8, v9
	global_store_dwordx4 v247, v[226:229], s[16:17]
	s_waitcnt vmcnt(15)
	v_cvt_f32_ubyte0_e32 v2, v204
	v_cvt_f32_ubyte1_e32 v3, v204
	v_cvt_f32_ubyte2_e32 v4, v204
	v_cvt_f32_ubyte3_e32 v5, v204
	v_cvt_f32_ubyte0_e32 v6, v205
	v_cvt_f32_ubyte1_e32 v7, v205
	v_cvt_f32_ubyte2_e32 v8, v205
	v_cvt_f32_ubyte3_e32 v9, v205
	v_pk_mul_f32 v[2:3], v[2:3], s[22:23] op_sel_hi:[1,0]
	v_pk_mul_f32 v[4:5], v[4:5], s[22:23] op_sel_hi:[1,0]
	v_pk_mul_f32 v[6:7], v[6:7], s[22:23] op_sel_hi:[1,0]
	v_pk_mul_f32 v[8:9], v[8:9], s[22:23] op_sel_hi:[1,0]
	v_pk_mul_f32 v[2:3], v[122:123], v[2:3]
	v_pk_mul_f32 v[4:5], v[124:125], v[4:5]
	v_pk_mul_f32 v[6:7], v[118:119], v[6:7]
	v_pk_mul_f32 v[8:9], v[120:121], v[8:9]
	v_cvt_pk_bf16_f32 v230, v2, v3
	v_cvt_pk_bf16_f32 v231, v4, v5
	v_cvt_pk_bf16_f32 v232, v6, v7
	v_cvt_pk_bf16_f32 v233, v8, v9
	global_store_dwordx4 v247, v[230:233], s[16:17] offset:256
	s_waitcnt vmcnt(15)
; __device__ __forceinline__ unsigned pk2(float lo, float hi) { f32x2 v = {lo, hi}; bf16x2_t b = __builtin_convertvector(v, bf16x2_t); return __builtin_bit_cast(unsigned, b); }
;     static __device__ __forceinline__ float ub(unsigned w, int i) { return (float)((w >> (8 * i)) & 0xffu); }
;     __device__ __forceinline__ void chain(Acc& acc, const Unit& u, int wr, int wc, int fr, int fq) const {
;     ...
; #pragma unroll
;                         for (int e = 0; e < 8; ++e) sc[e] = ub(e < 4 ? gg.x : gg.y, e & 3) * (1.0f / 255.0f);
;                     }
;                     f32x4 a0 = acc[ai][bj][m][0], a1 = acc[ai][bj][m][1];
;                     a0 *= (f32x4){sc[0], sc[1], sc[2], sc[3]}; a1 *= (f32x4){sc[4], sc[5], sc[6], sc[7]};
;                     if (sub < 2) { acc[ai][bj][m][0] = a0; acc[ai][bj][m][1] = a1; }
;                     else { u32x4 w; w.x = pk2(a0[0], a0[1]); w.y = pk2(a0[2], a0[3]); w.z = pk2(a1[0], a1[1]); w.w = pk2(a1[2], a1[3]);
;                         *(u32x4*)(MERGED + (size_t)(row0 + ai * HALF + m * 16) * DM + col0 + bj * HALF) = w; } }
	v_cvt_f32_ubyte0_e32 v2, v210
	v_cvt_f32_ubyte1_e32 v3, v210
	v_cvt_f32_ubyte2_e32 v4, v210
	v_cvt_f32_ubyte3_e32 v5, v210
	v_cvt_f32_ubyte0_e32 v6, v211
	v_cvt_f32_ubyte1_e32 v7, v211
	v_cvt_f32_ubyte2_e32 v8, v211
	v_cvt_f32_ubyte3_e32 v9, v211
	v_pk_mul_f32 v[2:3], v[2:3], s[22:23] op_sel_hi:[1,0]
	v_pk_mul_f32 v[4:5], v[4:5], s[22:23] op_sel_hi:[1,0]
	v_pk_mul_f32 v[6:7], v[6:7], s[22:23] op_sel_hi:[1,0]
	v_pk_mul_f32 v[8:9], v[8:9], s[22:23] op_sel_hi:[1,0]
	v_pk_mul_f32 v[2:3], v[106:107], v[2:3]
	v_pk_mul_f32 v[4:5], v[108:109], v[4:5]
	v_pk_mul_f32 v[6:7], v[102:103], v[6:7]
	v_pk_mul_f32 v[8:9], v[104:105], v[8:9]
	v_cvt_pk_bf16_f32 v226, v2, v3
	v_cvt_pk_bf16_f32 v227, v4, v5
	v_cvt_pk_bf16_f32 v228, v6, v7
	v_cvt_pk_bf16_f32 v229, v8, v9
	global_store_dwordx4 v248, v[226:229], s[16:17]
	s_waitcnt vmcnt(15)
	v_cvt_f32_ubyte0_e32 v2, v212
	v_cvt_f32_ubyte1_e32 v3, v212
	v_cvt_f32_ubyte2_e32 v4, v212
	v_cvt_f32_ubyte3_e32 v5, v212
	v_cvt_f32_ubyte0_e32 v6, v213
	v_cvt_f32_ubyte1_e32 v7, v213
	v_cvt_f32_ubyte2_e32 v8, v213
	v_cvt_f32_ubyte3_e32 v9, v213
	v_pk_mul_f32 v[2:3], v[2:3], s[22:23] op_sel_hi:[1,0]
	v_pk_mul_f32 v[4:5], v[4:5], s[22:23] op_sel_hi:[1,0]
	v_pk_mul_f32 v[6:7], v[6:7], s[22:23] op_sel_hi:[1,0]
	v_pk_mul_f32 v[8:9], v[8:9], s[22:23] op_sel_hi:[1,0]
	v_pk_mul_f32 v[2:3], v[90:91], v[2:3]
	v_pk_mul_f32 v[4:5], v[92:93], v[4:5]
	v_pk_mul_f32 v[6:7], v[86:87], v[6:7]
	v_pk_mul_f32 v[8:9], v[88:89], v[8:9]
	v_cvt_pk_bf16_f32 v230, v2, v3
	v_cvt_pk_bf16_f32 v231, v4, v5
	v_cvt_pk_bf16_f32 v232, v6, v7
	v_cvt_pk_bf16_f32 v233, v8, v9
	global_store_dwordx4 v248, v[230:233], s[16:17] offset:256
	s_waitcnt vmcnt(15)
	v_cvt_f32_ubyte0_e32 v2, v214
	v_cvt_f32_ubyte1_e32 v3, v214
	v_cvt_f32_ubyte2_e32 v4, v214
	v_cvt_f32_ubyte3_e32 v5, v214
	v_cvt_f32_ubyte0_e32 v6, v215
	v_cvt_f32_ubyte1_e32 v7, v215
	v_cvt_f32_ubyte2_e32 v8, v215
	v_cvt_f32_ubyte3_e32 v9, v215
	v_pk_mul_f32 v[2:3], v[2:3], s[22:23] op_sel_hi:[1,0]
	v_pk_mul_f32 v[4:5], v[4:5], s[22:23] op_sel_hi:[1,0]
	v_pk_mul_f32 v[6:7], v[6:7], s[22:23] op_sel_hi:[1,0]
	v_pk_mul_f32 v[8:9], v[8:9], s[22:23] op_sel_hi:[1,0]
	v_pk_mul_f32 v[2:3], v[74:75], v[2:3]
	v_pk_mul_f32 v[4:5], v[76:77], v[4:5]
	v_pk_mul_f32 v[6:7], v[70:71], v[6:7]
	v_pk_mul_f32 v[8:9], v[72:73], v[8:9]
	v_cvt_pk_bf16_f32 v226, v2, v3
	v_cvt_pk_bf16_f32 v227, v4, v5
	v_cvt_pk_bf16_f32 v228, v6, v7
	v_cvt_pk_bf16_f32 v229, v8, v9
	global_store_dwordx4 v249, v[226:229], s[16:17]
	s_waitcnt vmcnt(15)
	v_cvt_f32_ubyte0_e32 v2, v216
	v_cvt_f32_ubyte1_e32 v3, v216
	v_cvt_f32_ubyte2_e32 v4, v216
	v_cvt_f32_ubyte3_e32 v5, v216
	v_cvt_f32_ubyte0_e32 v6, v217
	v_cvt_f32_ubyte1_e32 v7, v217
	v_cvt_f32_ubyte2_e32 v8, v217
	v_cvt_f32_ubyte3_e32 v9, v217
	v_pk_mul_f32 v[2:3], v[2:3], s[22:23] op_sel_hi:[1,0]
	v_pk_mul_f32 v[4:5], v[4:5], s[22:23] op_sel_hi:[1,0]
	v_pk_mul_f32 v[6:7], v[6:7], s[22:23] op_sel_hi:[1,0]
	v_pk_mul_f32 v[8:9], v[8:9], s[22:23] op_sel_hi:[1,0]
	v_pk_mul_f32 v[2:3], v[58:59], v[2:3]
	v_pk_mul_f32 v[4:5], v[60:61], v[4:5]
	v_pk_mul_f32 v[6:7], v[54:55], v[6:7]
	v_pk_mul_f32 v[8:9], v[56:57], v[8:9]
	v_cvt_pk_bf16_f32 v230, v2, v3
	v_cvt_pk_bf16_f32 v231, v4, v5
	v_cvt_pk_bf16_f32 v232, v6, v7
	v_cvt_pk_bf16_f32 v233, v8, v9
	global_store_dwordx4 v249, v[230:233], s[16:17] offset:256
	s_waitcnt vmcnt(15)
	v_cvt_f32_ubyte0_e32 v2, v218
	v_cvt_f32_ubyte1_e32 v3, v218
	v_cvt_f32_ubyte2_e32 v4, v218
	v_cvt_f32_ubyte3_e32 v5, v218
	v_cvt_f32_ubyte0_e32 v6, v219
	v_cvt_f32_ubyte1_e32 v7, v219
	v_cvt_f32_ubyte2_e32 v8, v219
	v_cvt_f32_ubyte3_e32 v9, v219
	v_pk_mul_f32 v[2:3], v[2:3], s[22:23] op_sel_hi:[1,0]
	v_pk_mul_f32 v[4:5], v[4:5], s[22:23] op_sel_hi:[1,0]
	v_pk_mul_f32 v[6:7], v[6:7], s[22:23] op_sel_hi:[1,0]
	v_pk_mul_f32 v[8:9], v[8:9], s[22:23] op_sel_hi:[1,0]
	v_pk_mul_f32 v[2:3], v[42:43], v[2:3]
	v_pk_mul_f32 v[4:5], v[44:45], v[4:5]
	v_pk_mul_f32 v[6:7], v[38:39], v[6:7]
	v_pk_mul_f32 v[8:9], v[40:41], v[8:9]
	v_cvt_pk_bf16_f32 v226, v2, v3
	v_cvt_pk_bf16_f32 v227, v4, v5
	v_cvt_pk_bf16_f32 v228, v6, v7
	v_cvt_pk_bf16_f32 v229, v8, v9
	global_store_dwordx4 v250, v[226:229], s[16:17]
	s_waitcnt vmcnt(15)
	v_cvt_f32_ubyte0_e32 v2, v220
	v_cvt_f32_ubyte1_e32 v3, v220
	v_cvt_f32_ubyte2_e32 v4, v220
	v_cvt_f32_ubyte3_e32 v5, v220
	v_cvt_f32_ubyte0_e32 v6, v221
	v_cvt_f32_ubyte1_e32 v7, v221
	v_cvt_f32_ubyte2_e32 v8, v221
	v_cvt_f32_ubyte3_e32 v9, v221
	v_pk_mul_f32 v[2:3], v[2:3], s[22:23] op_sel_hi:[1,0]
	v_pk_mul_f32 v[4:5], v[4:5], s[22:23] op_sel_hi:[1,0]
	v_pk_mul_f32 v[6:7], v[6:7], s[22:23] op_sel_hi:[1,0]
	v_pk_mul_f32 v[8:9], v[8:9], s[22:23] op_sel_hi:[1,0]
	v_pk_mul_f32 v[2:3], v[34:35], v[2:3]
	v_pk_mul_f32 v[4:5], v[36:37], v[4:5]
	v_pk_mul_f32 v[6:7], v[30:31], v[6:7]
	v_pk_mul_f32 v[8:9], v[32:33], v[8:9]
	v_cvt_pk_bf16_f32 v230, v2, v3
	v_cvt_pk_bf16_f32 v231, v4, v5
	v_cvt_pk_bf16_f32 v232, v6, v7
	v_cvt_pk_bf16_f32 v233, v8, v9
	global_store_dwordx4 v250, v[230:233], s[16:17] offset:256
	s_waitcnt vmcnt(15)
	v_cvt_f32_ubyte0_e32 v2, v222
	v_cvt_f32_ubyte1_e32 v3, v222
	v_cvt_f32_ubyte2_e32 v4, v222
	v_cvt_f32_ubyte3_e32 v5, v222
	v_cvt_f32_ubyte0_e32 v6, v223
	v_cvt_f32_ubyte1_e32 v7, v223
	v_cvt_f32_ubyte2_e32 v8, v223
	v_cvt_f32_ubyte3_e32 v9, v223
	v_pk_mul_f32 v[2:3], v[2:3], s[22:23] op_sel_hi:[1,0]
	v_pk_mul_f32 v[4:5], v[4:5], s[22:23] op_sel_hi:[1,0]
	v_pk_mul_f32 v[6:7], v[6:7], s[22:23] op_sel_hi:[1,0]
	v_pk_mul_f32 v[8:9], v[8:9], s[22:23] op_sel_hi:[1,0]
	v_pk_mul_f32 v[2:3], v[26:27], v[2:3]
	v_pk_mul_f32 v[4:5], v[28:29], v[4:5]
	v_pk_mul_f32 v[6:7], v[22:23], v[6:7]
	v_pk_mul_f32 v[8:9], v[24:25], v[8:9]
	v_cvt_pk_bf16_f32 v226, v2, v3
	v_cvt_pk_bf16_f32 v227, v4, v5
	v_cvt_pk_bf16_f32 v228, v6, v7
	v_cvt_pk_bf16_f32 v229, v8, v9
	global_store_dwordx4 v251, v[226:229], s[16:17]
	s_waitcnt vmcnt(15)
	v_cvt_f32_ubyte0_e32 v2, v224
	v_cvt_f32_ubyte1_e32 v3, v224
	v_cvt_f32_ubyte2_e32 v4, v224
	v_cvt_f32_ubyte3_e32 v5, v224
	v_cvt_f32_ubyte0_e32 v6, v225
	v_cvt_f32_ubyte1_e32 v7, v225
	v_cvt_f32_ubyte2_e32 v8, v225
	v_cvt_f32_ubyte3_e32 v9, v225
	v_pk_mul_f32 v[2:3], v[2:3], s[22:23] op_sel_hi:[1,0]
	v_pk_mul_f32 v[4:5], v[4:5], s[22:23] op_sel_hi:[1,0]
	v_pk_mul_f32 v[6:7], v[6:7], s[22:23] op_sel_hi:[1,0]
	v_pk_mul_f32 v[8:9], v[8:9], s[22:23] op_sel_hi:[1,0]
	v_pk_mul_f32 v[2:3], v[18:19], v[2:3]
	v_pk_mul_f32 v[4:5], v[20:21], v[4:5]
	v_pk_mul_f32 v[6:7], v[14:15], v[6:7]
	v_pk_mul_f32 v[8:9], v[16:17], v[8:9]
	v_cvt_pk_bf16_f32 v230, v2, v3
	v_cvt_pk_bf16_f32 v231, v4, v5
	v_cvt_pk_bf16_f32 v232, v6, v7
	v_cvt_pk_bf16_f32 v233, v8, v9
	global_store_dwordx4 v251, v[230:233], s[16:17] offset:256

; template <class Epi, class Sched, bool ALIGN_EPI, bool SP2>
; __device__ __forceinline__ void gemm_phase(LAS unsigned char* lds, const int K, const Sched& S, const Epi& E) {
;     ...
;         if (!(Epi::CHAIN && nxt.sub != 0))
; #pragma unroll
;         for (int a = 0; a < 2; ++a)
; #pragma unroll
;             for (int b = 0; b < 2; ++b)
; #pragma unroll
;                 for (int m = 0; m < 4; ++m)
; #pragma unroll
;                     for (int n = 0; n < 2; ++n) acc[a][b][m][n] = (f32x4){0.f, 0.f, 0.f, 0.f};
.LBB0_974:
	v_mov_b32_e32 v11, v10
	v_mov_b64_e32 v[14:15], v[10:11]
	v_mov_b64_e32 v[16:17], v[10:11]
	v_mov_b64_e32 v[18:19], v[10:11]
	v_mov_b64_e32 v[20:21], v[10:11]
	v_mov_b64_e32 v[22:23], v[10:11]
	v_mov_b64_e32 v[24:25], v[10:11]
	v_mov_b64_e32 v[26:27], v[10:11]
	v_mov_b64_e32 v[28:29], v[10:11]
	v_mov_b64_e32 v[30:31], v[10:11]
	v_mov_b64_e32 v[32:33], v[10:11]
	v_mov_b64_e32 v[34:35], v[10:11]
	v_mov_b64_e32 v[36:37], v[10:11]
	v_mov_b64_e32 v[38:39], v[10:11]
	v_mov_b64_e32 v[40:41], v[10:11]
	v_mov_b64_e32 v[42:43], v[10:11]
	v_mov_b64_e32 v[44:45], v[10:11]
	v_mov_b64_e32 v[54:55], v[10:11]
	v_mov_b64_e32 v[56:57], v[10:11]
	v_mov_b64_e32 v[58:59], v[10:11]
	v_mov_b64_e32 v[60:61], v[10:11]
	v_mov_b64_e32 v[62:63], v[10:11]
	v_mov_b64_e32 v[64:65], v[10:11]
	v_mov_b64_e32 v[66:67], v[10:11]
	v_mov_b64_e32 v[68:69], v[10:11]
	v_mov_b64_e32 v[70:71], v[10:11]
	v_mov_b64_e32 v[72:73], v[10:11]
	v_mov_b64_e32 v[74:75], v[10:11]
	v_mov_b64_e32 v[76:77], v[10:11]
	v_mov_b64_e32 v[86:87], v[10:11]
	v_mov_b64_e32 v[88:89], v[10:11]
	v_mov_b64_e32 v[90:91], v[10:11]
	v_mov_b64_e32 v[92:93], v[10:11]
	v_mov_b64_e32 v[94:95], v[10:11]
	v_mov_b64_e32 v[96:97], v[10:11]
	v_mov_b64_e32 v[98:99], v[10:11]
	v_mov_b64_e32 v[100:101], v[10:11]
	v_mov_b64_e32 v[102:103], v[10:11]
	v_mov_b64_e32 v[104:105], v[10:11]
	v_mov_b64_e32 v[106:107], v[10:11]
	v_mov_b64_e32 v[108:109], v[10:11]
	v_mov_b64_e32 v[118:119], v[10:11]
	v_mov_b64_e32 v[120:121], v[10:11]
	v_mov_b64_e32 v[122:123], v[10:11]
	v_mov_b64_e32 v[124:125], v[10:11]
	v_mov_b64_e32 v[126:127], v[10:11]
	v_mov_b64_e32 v[128:129], v[10:11]
	v_mov_b64_e32 v[130:131], v[10:11]
	v_mov_b64_e32 v[132:133], v[10:11]
	v_mov_b64_e32 v[134:135], v[10:11]
	v_mov_b64_e32 v[136:137], v[10:11]
	v_mov_b64_e32 v[138:139], v[10:11]
	v_mov_b64_e32 v[140:141], v[10:11]
	v_mov_b64_e32 v[150:151], v[10:11]
	v_mov_b64_e32 v[152:153], v[10:11]
	v_mov_b64_e32 v[154:155], v[10:11]
	v_mov_b64_e32 v[156:157], v[10:11]
	v_mov_b64_e32 v[158:159], v[10:11]
	v_mov_b64_e32 v[160:161], v[10:11]
	v_mov_b64_e32 v[162:163], v[10:11]
	v_mov_b64_e32 v[164:165], v[10:11]
	v_mov_b64_e32 v[166:167], v[10:11]
	v_mov_b64_e32 v[168:169], v[10:11]
	v_mov_b64_e32 v[170:171], v[10:11]
	v_mov_b64_e32 v[172:173], v[10:11]
	s_andn2_b64 vcc, exec, s[8:9]
	s_cbranch_vccnz .LBB0_859
